# GEMM tile loops: accumulator clearing with v_pk_mov_b32 register pairs (63 instead of 126 moves per tile)
# speedup vs baseline: 1.0144x; 1.0072x over previous
; template <class Epi, class Sched, bool ALIGN_EPI = false, bool SP2 = false>
; __device__ __forceinline__ void gemm_phase(PG8_LAS unsigned char* lds, const Gemm g, const Sched& S, const Epi& E, int wv) {
;     ...
;         const char* nA = has_next ? (const char*)g.A + (size_t)nxt.pm * tstepA : cA; const char* nB = has_next ? (const char*)g.Bt + (size_t)nxt.pn * tstepB : cB;
; #pragma unroll 1
;         for (int t = 0; t < nt; t += 2) {
;             const bool last = (t == nt - 2);
;             const char* a1 = cA + (size_t)(t + 1) * kstep;
;             const char* a2 = last ? nA : cA + (size_t)(t + 2) * kstep; const char* b2 = last ? nB : cB + (size_t)(t + 2) * kstep;
;             const char* a3 = a2 + kstep; const char* b3 = b2 + kstep;
;     ...
; #pragma unroll
;         for (int a = 0; a < 2; ++a)
; #pragma unroll
;             for (int b = 0; b < 2; ++b)
; #pragma unroll
;                 for (int m = 0; m < 4; ++m)
; #pragma unroll
;                     for (int n = 0; n < 2; ++n) acc[a][b][m][n] = (f32x4){0.f, 0.f, 0.f, 0.f};
.LBB0_662:
	s_ashr_i32 s45, s44, 31
	s_lshl_b64 s[46:47], s[44:45], 19
	s_add_u32 s46, s13, s46
	s_addc_u32 s47, s14, s47
	s_and_b64 s[48:49], s[16:17], exec
	s_cselect_b32 s15, s47, s35
	s_cselect_b32 s19, s46, s34
	s_ashr_i32 s43, s42, 31
	s_lshl_b64 s[48:49], s[42:43], 19
	s_add_u32 s48, s52, s48
	s_addc_u32 s49, s53, s49
	s_and_b64 s[50:51], s[16:17], exec
	s_cselect_b32 s43, s49, s3
	s_cselect_b32 s45, s48, s2
	s_add_u32 s34, s34, 0x40080
	s_addc_u32 s35, s35, 0
	s_add_u32 s96, s2, 0x100
	v_mov_b32_e32 v2, 0
	s_addc_u32 s97, s3, 0
	s_mov_b32 vcc_lo, -2
	v_mov_b32_e32 v3, v2
	v_pk_mov_b32 v[4:5], v[2:3], v[2:3]
	v_pk_mov_b32 v[6:7], v[2:3], v[2:3]
	v_pk_mov_b32 v[8:9], v[2:3], v[2:3]
	v_pk_mov_b32 v[18:19], v[2:3], v[2:3]
	v_pk_mov_b32 v[20:21], v[2:3], v[2:3]
	v_pk_mov_b32 v[22:23], v[2:3], v[2:3]
	v_pk_mov_b32 v[24:25], v[2:3], v[2:3]
	v_pk_mov_b32 v[34:35], v[2:3], v[2:3]
	v_pk_mov_b32 v[36:37], v[2:3], v[2:3]
	v_pk_mov_b32 v[38:39], v[2:3], v[2:3]
	v_pk_mov_b32 v[40:41], v[2:3], v[2:3]
	v_pk_mov_b32 v[50:51], v[2:3], v[2:3]
	v_pk_mov_b32 v[52:53], v[2:3], v[2:3]
	v_pk_mov_b32 v[54:55], v[2:3], v[2:3]
	v_pk_mov_b32 v[56:57], v[2:3], v[2:3]
	v_pk_mov_b32 v[10:11], v[2:3], v[2:3]
	v_pk_mov_b32 v[12:13], v[2:3], v[2:3]
	v_pk_mov_b32 v[14:15], v[2:3], v[2:3]
	v_pk_mov_b32 v[16:17], v[2:3], v[2:3]
	v_pk_mov_b32 v[26:27], v[2:3], v[2:3]
	v_pk_mov_b32 v[28:29], v[2:3], v[2:3]
	v_pk_mov_b32 v[30:31], v[2:3], v[2:3]
	v_pk_mov_b32 v[32:33], v[2:3], v[2:3]
	v_pk_mov_b32 v[42:43], v[2:3], v[2:3]
	v_pk_mov_b32 v[44:45], v[2:3], v[2:3]
	v_pk_mov_b32 v[46:47], v[2:3], v[2:3]
	v_pk_mov_b32 v[48:49], v[2:3], v[2:3]
	v_pk_mov_b32 v[58:59], v[2:3], v[2:3]
	v_pk_mov_b32 v[60:61], v[2:3], v[2:3]
	v_pk_mov_b32 v[62:63], v[2:3], v[2:3]
	v_pk_mov_b32 v[64:65], v[2:3], v[2:3]
	v_pk_mov_b32 v[66:67], v[2:3], v[2:3]
	v_pk_mov_b32 v[68:69], v[2:3], v[2:3]
	v_pk_mov_b32 v[70:71], v[2:3], v[2:3]
	v_pk_mov_b32 v[72:73], v[2:3], v[2:3]
	v_pk_mov_b32 v[82:83], v[2:3], v[2:3]
	v_pk_mov_b32 v[84:85], v[2:3], v[2:3]
	v_pk_mov_b32 v[86:87], v[2:3], v[2:3]
	v_pk_mov_b32 v[88:89], v[2:3], v[2:3]
	v_pk_mov_b32 v[98:99], v[2:3], v[2:3]
	v_pk_mov_b32 v[100:101], v[2:3], v[2:3]
	v_pk_mov_b32 v[102:103], v[2:3], v[2:3]
	v_pk_mov_b32 v[104:105], v[2:3], v[2:3]
	v_pk_mov_b32 v[114:115], v[2:3], v[2:3]
	v_pk_mov_b32 v[116:117], v[2:3], v[2:3]
	v_pk_mov_b32 v[118:119], v[2:3], v[2:3]
	v_pk_mov_b32 v[120:121], v[2:3], v[2:3]
	v_pk_mov_b32 v[74:75], v[2:3], v[2:3]
	v_pk_mov_b32 v[76:77], v[2:3], v[2:3]
	v_pk_mov_b32 v[78:79], v[2:3], v[2:3]
	v_pk_mov_b32 v[80:81], v[2:3], v[2:3]
	v_pk_mov_b32 v[90:91], v[2:3], v[2:3]
	v_pk_mov_b32 v[92:93], v[2:3], v[2:3]
	v_pk_mov_b32 v[94:95], v[2:3], v[2:3]
	v_pk_mov_b32 v[96:97], v[2:3], v[2:3]
	v_pk_mov_b32 v[106:107], v[2:3], v[2:3]
	v_pk_mov_b32 v[108:109], v[2:3], v[2:3]
	v_pk_mov_b32 v[110:111], v[2:3], v[2:3]
	v_pk_mov_b32 v[112:113], v[2:3], v[2:3]
	v_pk_mov_b32 v[122:123], v[2:3], v[2:3]
	v_pk_mov_b32 v[124:125], v[2:3], v[2:3]
	v_pk_mov_b32 v[126:127], v[2:3], v[2:3]
	v_pk_mov_b32 v[128:129], v[2:3], v[2:3]

; template <class Epi, class Sched, bool ALIGN_EPI = false, bool SP2 = false>
; __device__ __forceinline__ void gemm_phase(PG8_LAS unsigned char* lds, const Gemm g, const Sched& S, const Epi& E, int wv) {
;     ...
;         const char* nA = has_next ? (const char*)g.A + (size_t)nxt.pm * tstepA : cA; const char* nB = has_next ? (const char*)g.Bt + (size_t)nxt.pn * tstepB : cB;
; #pragma unroll 1
;         for (int t = 0; t < nt; t += 2) {
;             const bool last = (t == nt - 2);
;             const char* a1 = cA + (size_t)(t + 1) * kstep;
;             const char* a2 = last ? nA : cA + (size_t)(t + 2) * kstep; const char* b2 = last ? nB : cB + (size_t)(t + 2) * kstep;
;             const char* a3 = a2 + kstep; const char* b3 = b2 + kstep;
;     ...
; #pragma unroll
;         for (int a = 0; a < 2; ++a)
; #pragma unroll
;             for (int b = 0; b < 2; ++b)
; #pragma unroll
;                 for (int m = 0; m < 4; ++m)
; #pragma unroll
;                     for (int n = 0; n < 2; ++n) acc[a][b][m][n] = (f32x4){0.f, 0.f, 0.f, 0.f};
.LBB0_887:
	s_ashr_i32 s43, s42, 31
	s_lshl_b64 s[2:3], s[42:43], 17
	v_readlane_b32 s7, v254, 60
	s_add_u32 s46, s7, s2
	v_readlane_b32 s2, v254, 61
	s_addc_u32 s47, s2, s3
	s_and_b64 s[2:3], s[18:19], exec
	v_mov_b32_e32 v2, 0
	s_cselect_b32 s43, s47, s35
	s_cselect_b32 s24, s46, s34
	s_mov_b64 s[50:51], 0
	s_mov_b64 s[18:19], -1
	s_mov_b64 s[2:3], 0
	v_mov_b32_e32 v3, v2
	v_pk_mov_b32 v[4:5], v[2:3], v[2:3]
	v_pk_mov_b32 v[6:7], v[2:3], v[2:3]
	v_pk_mov_b32 v[8:9], v[2:3], v[2:3]
	v_pk_mov_b32 v[18:19], v[2:3], v[2:3]
	v_pk_mov_b32 v[20:21], v[2:3], v[2:3]
	v_pk_mov_b32 v[22:23], v[2:3], v[2:3]
	v_pk_mov_b32 v[24:25], v[2:3], v[2:3]
	v_pk_mov_b32 v[34:35], v[2:3], v[2:3]
	v_pk_mov_b32 v[36:37], v[2:3], v[2:3]
	v_pk_mov_b32 v[38:39], v[2:3], v[2:3]
	v_pk_mov_b32 v[40:41], v[2:3], v[2:3]
	v_pk_mov_b32 v[50:51], v[2:3], v[2:3]
	v_pk_mov_b32 v[52:53], v[2:3], v[2:3]
	v_pk_mov_b32 v[54:55], v[2:3], v[2:3]
	v_pk_mov_b32 v[56:57], v[2:3], v[2:3]
	v_pk_mov_b32 v[10:11], v[2:3], v[2:3]
	v_pk_mov_b32 v[12:13], v[2:3], v[2:3]
	v_pk_mov_b32 v[14:15], v[2:3], v[2:3]
	v_pk_mov_b32 v[16:17], v[2:3], v[2:3]
	v_pk_mov_b32 v[26:27], v[2:3], v[2:3]
	v_pk_mov_b32 v[28:29], v[2:3], v[2:3]
	v_pk_mov_b32 v[30:31], v[2:3], v[2:3]
	v_pk_mov_b32 v[32:33], v[2:3], v[2:3]
	v_pk_mov_b32 v[42:43], v[2:3], v[2:3]
	v_pk_mov_b32 v[44:45], v[2:3], v[2:3]
	v_pk_mov_b32 v[46:47], v[2:3], v[2:3]
	v_pk_mov_b32 v[48:49], v[2:3], v[2:3]
	v_pk_mov_b32 v[58:59], v[2:3], v[2:3]
	v_pk_mov_b32 v[60:61], v[2:3], v[2:3]
	v_pk_mov_b32 v[62:63], v[2:3], v[2:3]
	v_pk_mov_b32 v[64:65], v[2:3], v[2:3]
	v_pk_mov_b32 v[66:67], v[2:3], v[2:3]
	v_pk_mov_b32 v[68:69], v[2:3], v[2:3]
	v_pk_mov_b32 v[70:71], v[2:3], v[2:3]
	v_pk_mov_b32 v[72:73], v[2:3], v[2:3]
	v_pk_mov_b32 v[82:83], v[2:3], v[2:3]
	v_pk_mov_b32 v[84:85], v[2:3], v[2:3]
	v_pk_mov_b32 v[86:87], v[2:3], v[2:3]
	v_pk_mov_b32 v[88:89], v[2:3], v[2:3]
	v_pk_mov_b32 v[98:99], v[2:3], v[2:3]
	v_pk_mov_b32 v[100:101], v[2:3], v[2:3]
	v_pk_mov_b32 v[102:103], v[2:3], v[2:3]
	v_pk_mov_b32 v[104:105], v[2:3], v[2:3]
	v_pk_mov_b32 v[114:115], v[2:3], v[2:3]
	v_pk_mov_b32 v[116:117], v[2:3], v[2:3]
	v_pk_mov_b32 v[118:119], v[2:3], v[2:3]
	v_pk_mov_b32 v[120:121], v[2:3], v[2:3]
	v_pk_mov_b32 v[74:75], v[2:3], v[2:3]
	v_pk_mov_b32 v[76:77], v[2:3], v[2:3]
	v_pk_mov_b32 v[78:79], v[2:3], v[2:3]
	v_pk_mov_b32 v[80:81], v[2:3], v[2:3]
	v_pk_mov_b32 v[90:91], v[2:3], v[2:3]
	v_pk_mov_b32 v[92:93], v[2:3], v[2:3]
	v_pk_mov_b32 v[94:95], v[2:3], v[2:3]
	v_pk_mov_b32 v[96:97], v[2:3], v[2:3]
	v_pk_mov_b32 v[106:107], v[2:3], v[2:3]
	v_pk_mov_b32 v[108:109], v[2:3], v[2:3]
	v_pk_mov_b32 v[110:111], v[2:3], v[2:3]
	v_pk_mov_b32 v[112:113], v[2:3], v[2:3]
	v_pk_mov_b32 v[122:123], v[2:3], v[2:3]
	v_pk_mov_b32 v[124:125], v[2:3], v[2:3]
	v_pk_mov_b32 v[126:127], v[2:3], v[2:3]
	v_pk_mov_b32 v[128:129], v[2:3], v[2:3]

; template <class Epi, class Sched, bool ALIGN_EPI = false, bool SP2 = false>
; __device__ __forceinline__ void gemm_phase(PG8_LAS unsigned char* lds, const Gemm g, const Sched& S, const Epi& E, int wv) {
;     ...
;         const char* nA = has_next ? (const char*)g.A + (size_t)nxt.pm * tstepA : cA; const char* nB = has_next ? (const char*)g.Bt + (size_t)nxt.pn * tstepB : cB;
; #pragma unroll 1
;         for (int t = 0; t < nt; t += 2) {
;             const bool last = (t == nt - 2);
;             const char* a1 = cA + (size_t)(t + 1) * kstep;
;             const char* a2 = last ? nA : cA + (size_t)(t + 2) * kstep; const char* b2 = last ? nB : cB + (size_t)(t + 2) * kstep;
;             const char* a3 = a2 + kstep; const char* b3 = b2 + kstep;
;     ...
; #pragma unroll
;         for (int a = 0; a < 2; ++a)
; #pragma unroll
;             for (int b = 0; b < 2; ++b)
; #pragma unroll
;                 for (int m = 0; m < 4; ++m)
; #pragma unroll
;                     for (int n = 0; n < 2; ++n) acc[a][b][m][n] = (f32x4){0.f, 0.f, 0.f, 0.f};
.LBB0_1270:
	s_ashr_i32 s51, s50, 31
	s_lshl_b64 s[2:3], s[50:51], 17
	s_add_u32 s96, s24, s2
	s_addc_u32 s97, s25, s3
	s_and_b64 s[2:3], s[18:19], exec
	v_mov_b32_e32 v2, 0
	s_cselect_b32 s51, s97, s41
	s_cselect_b32 s44, s96, s40
	s_mov_b64 s[42:43], 0
	s_mov_b64 s[18:19], -1
	s_mov_b64 s[2:3], 0
	v_mov_b32_e32 v3, v2
	v_pk_mov_b32 v[4:5], v[2:3], v[2:3]
	v_pk_mov_b32 v[6:7], v[2:3], v[2:3]
	v_pk_mov_b32 v[8:9], v[2:3], v[2:3]
	v_pk_mov_b32 v[18:19], v[2:3], v[2:3]
	v_pk_mov_b32 v[20:21], v[2:3], v[2:3]
	v_pk_mov_b32 v[22:23], v[2:3], v[2:3]
	v_pk_mov_b32 v[24:25], v[2:3], v[2:3]
	v_pk_mov_b32 v[34:35], v[2:3], v[2:3]
	v_pk_mov_b32 v[36:37], v[2:3], v[2:3]
	v_pk_mov_b32 v[38:39], v[2:3], v[2:3]
	v_pk_mov_b32 v[40:41], v[2:3], v[2:3]
	v_pk_mov_b32 v[50:51], v[2:3], v[2:3]
	v_pk_mov_b32 v[52:53], v[2:3], v[2:3]
	v_pk_mov_b32 v[54:55], v[2:3], v[2:3]
	v_pk_mov_b32 v[56:57], v[2:3], v[2:3]
	v_pk_mov_b32 v[10:11], v[2:3], v[2:3]
	v_pk_mov_b32 v[12:13], v[2:3], v[2:3]
	v_pk_mov_b32 v[14:15], v[2:3], v[2:3]
	v_pk_mov_b32 v[16:17], v[2:3], v[2:3]
	v_pk_mov_b32 v[26:27], v[2:3], v[2:3]
	v_pk_mov_b32 v[28:29], v[2:3], v[2:3]
	v_pk_mov_b32 v[30:31], v[2:3], v[2:3]
	v_pk_mov_b32 v[32:33], v[2:3], v[2:3]
	v_pk_mov_b32 v[42:43], v[2:3], v[2:3]
	v_pk_mov_b32 v[44:45], v[2:3], v[2:3]
	v_pk_mov_b32 v[46:47], v[2:3], v[2:3]
	v_pk_mov_b32 v[48:49], v[2:3], v[2:3]
	v_pk_mov_b32 v[58:59], v[2:3], v[2:3]
	v_pk_mov_b32 v[60:61], v[2:3], v[2:3]
	v_pk_mov_b32 v[62:63], v[2:3], v[2:3]
	v_pk_mov_b32 v[64:65], v[2:3], v[2:3]
	v_pk_mov_b32 v[66:67], v[2:3], v[2:3]
	v_pk_mov_b32 v[68:69], v[2:3], v[2:3]
	v_pk_mov_b32 v[70:71], v[2:3], v[2:3]
	v_pk_mov_b32 v[72:73], v[2:3], v[2:3]
	v_pk_mov_b32 v[82:83], v[2:3], v[2:3]
	v_pk_mov_b32 v[84:85], v[2:3], v[2:3]
	v_pk_mov_b32 v[86:87], v[2:3], v[2:3]
	v_pk_mov_b32 v[88:89], v[2:3], v[2:3]
	v_pk_mov_b32 v[98:99], v[2:3], v[2:3]
	v_pk_mov_b32 v[100:101], v[2:3], v[2:3]
	v_pk_mov_b32 v[102:103], v[2:3], v[2:3]
	v_pk_mov_b32 v[104:105], v[2:3], v[2:3]
	v_pk_mov_b32 v[114:115], v[2:3], v[2:3]
	v_pk_mov_b32 v[116:117], v[2:3], v[2:3]
	v_pk_mov_b32 v[118:119], v[2:3], v[2:3]
	v_pk_mov_b32 v[120:121], v[2:3], v[2:3]
	v_pk_mov_b32 v[74:75], v[2:3], v[2:3]
	v_pk_mov_b32 v[76:77], v[2:3], v[2:3]
	v_pk_mov_b32 v[78:79], v[2:3], v[2:3]
	v_pk_mov_b32 v[80:81], v[2:3], v[2:3]
	v_pk_mov_b32 v[90:91], v[2:3], v[2:3]
	v_pk_mov_b32 v[92:93], v[2:3], v[2:3]
	v_pk_mov_b32 v[94:95], v[2:3], v[2:3]
	v_pk_mov_b32 v[96:97], v[2:3], v[2:3]
	v_pk_mov_b32 v[106:107], v[2:3], v[2:3]
	v_pk_mov_b32 v[108:109], v[2:3], v[2:3]
	v_pk_mov_b32 v[110:111], v[2:3], v[2:3]
	v_pk_mov_b32 v[112:113], v[2:3], v[2:3]
	v_pk_mov_b32 v[122:123], v[2:3], v[2:3]
	v_pk_mov_b32 v[124:125], v[2:3], v[2:3]
	v_pk_mov_b32 v[126:127], v[2:3], v[2:3]
	v_pk_mov_b32 v[128:129], v[2:3], v[2:3]

; template <class Epi, class Sched, bool ALIGN_EPI = false, bool SP2 = false>
; __device__ __forceinline__ void gemm_phase(PG8_LAS unsigned char* lds, const Gemm g, const Sched& S, const Epi& E, int wv) {
;     ...
;         const char* nA = has_next ? (const char*)g.A + (size_t)nxt.pm * tstepA : cA; const char* nB = has_next ? (const char*)g.Bt + (size_t)nxt.pn * tstepB : cB;
; #pragma unroll 1
;         for (int t = 0; t < nt; t += 2) {
;             const bool last = (t == nt - 2);
;             const char* a1 = cA + (size_t)(t + 1) * kstep;
;             const char* a2 = last ? nA : cA + (size_t)(t + 2) * kstep; const char* b2 = last ? nB : cB + (size_t)(t + 2) * kstep;
;             const char* a3 = a2 + kstep; const char* b3 = b2 + kstep;
;     ...
; #pragma unroll
;         for (int a = 0; a < 2; ++a)
; #pragma unroll
;             for (int b = 0; b < 2; ++b)
; #pragma unroll
;                 for (int m = 0; m < 4; ++m)
; #pragma unroll
;                     for (int n = 0; n < 2; ++n) acc[a][b][m][n] = (f32x4){0.f, 0.f, 0.f, 0.f};
.LBB0_1742:
	s_ashr_i32 s47, s46, 31
	s_lshl_b64 s[34:35], s[46:47], 19
	s_add_u32 s48, s13, s34
	s_addc_u32 s49, s14, s35
	s_and_b64 s[34:35], s[16:17], exec
	s_cselect_b32 s15, s49, s21
	s_cselect_b32 s19, s48, s20
	s_ashr_i32 s45, s44, 31
	s_lshl_b64 s[34:35], s[44:45], 19
	s_add_u32 s50, s40, s34
	s_addc_u32 s51, s41, s35
	s_and_b64 s[34:35], s[16:17], exec
	s_cselect_b32 s45, s51, s3
	s_cselect_b32 s47, s50, s2
	s_add_u32 s20, s20, 0x40080
	s_addc_u32 s21, s21, 0
	s_add_u32 s94, s2, 0x100
	v_mov_b32_e32 v2, 0
	s_addc_u32 s95, s3, 0
	s_mov_b32 s97, -2
	v_mov_b32_e32 v3, v2
	s_waitcnt lgkmcnt(0)
	v_pk_mov_b32 v[4:5], v[2:3], v[2:3]
	v_pk_mov_b32 v[6:7], v[2:3], v[2:3]
	v_pk_mov_b32 v[8:9], v[2:3], v[2:3]
	v_pk_mov_b32 v[18:19], v[2:3], v[2:3]
	v_pk_mov_b32 v[20:21], v[2:3], v[2:3]
	v_pk_mov_b32 v[22:23], v[2:3], v[2:3]
	v_pk_mov_b32 v[24:25], v[2:3], v[2:3]
	v_pk_mov_b32 v[34:35], v[2:3], v[2:3]
	v_pk_mov_b32 v[36:37], v[2:3], v[2:3]
	v_pk_mov_b32 v[38:39], v[2:3], v[2:3]
	v_pk_mov_b32 v[40:41], v[2:3], v[2:3]
	v_pk_mov_b32 v[50:51], v[2:3], v[2:3]
	v_pk_mov_b32 v[52:53], v[2:3], v[2:3]
	v_pk_mov_b32 v[54:55], v[2:3], v[2:3]
	v_pk_mov_b32 v[56:57], v[2:3], v[2:3]
	v_pk_mov_b32 v[10:11], v[2:3], v[2:3]
	v_pk_mov_b32 v[12:13], v[2:3], v[2:3]
	v_pk_mov_b32 v[14:15], v[2:3], v[2:3]
	v_pk_mov_b32 v[16:17], v[2:3], v[2:3]
	v_pk_mov_b32 v[26:27], v[2:3], v[2:3]
	v_pk_mov_b32 v[28:29], v[2:3], v[2:3]
	v_pk_mov_b32 v[30:31], v[2:3], v[2:3]
	v_pk_mov_b32 v[32:33], v[2:3], v[2:3]
	v_pk_mov_b32 v[42:43], v[2:3], v[2:3]
	v_pk_mov_b32 v[44:45], v[2:3], v[2:3]
	v_pk_mov_b32 v[46:47], v[2:3], v[2:3]
	v_pk_mov_b32 v[48:49], v[2:3], v[2:3]
	v_pk_mov_b32 v[58:59], v[2:3], v[2:3]
	v_pk_mov_b32 v[60:61], v[2:3], v[2:3]
	v_pk_mov_b32 v[62:63], v[2:3], v[2:3]
	v_pk_mov_b32 v[64:65], v[2:3], v[2:3]
	v_pk_mov_b32 v[66:67], v[2:3], v[2:3]
	v_pk_mov_b32 v[68:69], v[2:3], v[2:3]
	v_pk_mov_b32 v[70:71], v[2:3], v[2:3]
	v_pk_mov_b32 v[72:73], v[2:3], v[2:3]
	v_pk_mov_b32 v[82:83], v[2:3], v[2:3]
	v_pk_mov_b32 v[84:85], v[2:3], v[2:3]
	v_pk_mov_b32 v[86:87], v[2:3], v[2:3]
	v_pk_mov_b32 v[88:89], v[2:3], v[2:3]
	v_pk_mov_b32 v[98:99], v[2:3], v[2:3]
	v_pk_mov_b32 v[100:101], v[2:3], v[2:3]
	v_pk_mov_b32 v[102:103], v[2:3], v[2:3]
	v_pk_mov_b32 v[104:105], v[2:3], v[2:3]
	v_pk_mov_b32 v[114:115], v[2:3], v[2:3]
	v_pk_mov_b32 v[116:117], v[2:3], v[2:3]
	v_pk_mov_b32 v[118:119], v[2:3], v[2:3]
	v_pk_mov_b32 v[120:121], v[2:3], v[2:3]
	v_pk_mov_b32 v[74:75], v[2:3], v[2:3]
	v_pk_mov_b32 v[76:77], v[2:3], v[2:3]
	v_pk_mov_b32 v[78:79], v[2:3], v[2:3]
	v_pk_mov_b32 v[80:81], v[2:3], v[2:3]
	v_pk_mov_b32 v[90:91], v[2:3], v[2:3]
	v_pk_mov_b32 v[92:93], v[2:3], v[2:3]
	v_pk_mov_b32 v[94:95], v[2:3], v[2:3]
	v_pk_mov_b32 v[96:97], v[2:3], v[2:3]
	v_pk_mov_b32 v[106:107], v[2:3], v[2:3]
	v_pk_mov_b32 v[108:109], v[2:3], v[2:3]
	v_pk_mov_b32 v[110:111], v[2:3], v[2:3]
	v_pk_mov_b32 v[112:113], v[2:3], v[2:3]
	v_pk_mov_b32 v[122:123], v[2:3], v[2:3]
	v_pk_mov_b32 v[124:125], v[2:3], v[2:3]
	v_pk_mov_b32 v[126:127], v[2:3], v[2:3]
	v_pk_mov_b32 v[128:129], v[2:3], v[2:3]

; template <class Epi, class Sched, bool ALIGN_EPI = false, bool SP2 = false>
; __device__ __forceinline__ void gemm_phase(PG8_LAS unsigned char* lds, const Gemm g, const Sched& S, const Epi& E, int wv) {
;     ...
;         const char* nA = has_next ? (const char*)g.A + (size_t)nxt.pm * tstepA : cA; const char* nB = has_next ? (const char*)g.Bt + (size_t)nxt.pn * tstepB : cB;
; #pragma unroll 1
;         for (int t = 0; t < nt; t += 2) {
;             const bool last = (t == nt - 2);
;             const char* a1 = cA + (size_t)(t + 1) * kstep;
;             const char* a2 = last ? nA : cA + (size_t)(t + 2) * kstep; const char* b2 = last ? nB : cB + (size_t)(t + 2) * kstep;
;             const char* a3 = a2 + kstep; const char* b3 = b2 + kstep;
;     ...
; #pragma unroll
;         for (int a = 0; a < 2; ++a)
; #pragma unroll
;             for (int b = 0; b < 2; ++b)
; #pragma unroll
;                 for (int m = 0; m < 4; ++m)
; #pragma unroll
;                     for (int n = 0; n < 2; ++n) acc[a][b][m][n] = (f32x4){0.f, 0.f, 0.f, 0.f};
.LBB0_1892:
	s_ashr_i32 s39, s38, 31
	s_lshl_b64 s[42:43], s[38:39], 19
	s_add_u32 s44, s13, s42
	s_addc_u32 s45, s14, s43
	s_and_b64 s[42:43], s[16:17], exec
	s_cselect_b32 s39, s45, s41
	s_cselect_b32 s92, s44, s40
	s_ashr_i32 s37, s36, 31
	s_lshl_b64 s[42:43], s[36:37], 19
	s_add_u32 s46, s48, s42
	s_addc_u32 s47, s49, s43
	s_and_b64 s[42:43], s[16:17], exec
	s_cselect_b32 s37, s47, s3
	s_cselect_b32 s93, s46, s2
	s_add_u32 s40, s40, 0x40080
	s_addc_u32 s41, s41, 0
	s_add_u32 s94, s2, 0x100
	v_mov_b32_e32 v2, 0
	s_addc_u32 s95, s3, 0
	s_mov_b32 s96, -2
	v_mov_b32_e32 v3, v2
	v_pk_mov_b32 v[4:5], v[2:3], v[2:3]
	v_pk_mov_b32 v[6:7], v[2:3], v[2:3]
	v_pk_mov_b32 v[8:9], v[2:3], v[2:3]
	v_pk_mov_b32 v[18:19], v[2:3], v[2:3]
	v_pk_mov_b32 v[20:21], v[2:3], v[2:3]
	v_pk_mov_b32 v[22:23], v[2:3], v[2:3]
	v_pk_mov_b32 v[24:25], v[2:3], v[2:3]
	v_pk_mov_b32 v[66:67], v[2:3], v[2:3]
	v_pk_mov_b32 v[68:69], v[2:3], v[2:3]
	v_pk_mov_b32 v[70:71], v[2:3], v[2:3]
	v_pk_mov_b32 v[72:73], v[2:3], v[2:3]
	v_pk_mov_b32 v[82:83], v[2:3], v[2:3]
	v_pk_mov_b32 v[84:85], v[2:3], v[2:3]
	v_pk_mov_b32 v[86:87], v[2:3], v[2:3]
	v_pk_mov_b32 v[88:89], v[2:3], v[2:3]
	v_pk_mov_b32 v[10:11], v[2:3], v[2:3]
	v_pk_mov_b32 v[12:13], v[2:3], v[2:3]
	v_pk_mov_b32 v[14:15], v[2:3], v[2:3]
	v_pk_mov_b32 v[16:17], v[2:3], v[2:3]
	v_pk_mov_b32 v[26:27], v[2:3], v[2:3]
	v_pk_mov_b32 v[28:29], v[2:3], v[2:3]
	v_pk_mov_b32 v[30:31], v[2:3], v[2:3]
	v_pk_mov_b32 v[32:33], v[2:3], v[2:3]
	v_pk_mov_b32 v[74:75], v[2:3], v[2:3]
	v_pk_mov_b32 v[76:77], v[2:3], v[2:3]
	v_pk_mov_b32 v[78:79], v[2:3], v[2:3]
	v_pk_mov_b32 v[80:81], v[2:3], v[2:3]
	v_pk_mov_b32 v[90:91], v[2:3], v[2:3]
	v_pk_mov_b32 v[92:93], v[2:3], v[2:3]
	v_pk_mov_b32 v[94:95], v[2:3], v[2:3]
	v_pk_mov_b32 v[96:97], v[2:3], v[2:3]
	v_pk_mov_b32 v[98:99], v[2:3], v[2:3]
	v_pk_mov_b32 v[100:101], v[2:3], v[2:3]
	v_pk_mov_b32 v[102:103], v[2:3], v[2:3]
	v_pk_mov_b32 v[104:105], v[2:3], v[2:3]
	v_pk_mov_b32 v[114:115], v[2:3], v[2:3]
	v_pk_mov_b32 v[116:117], v[2:3], v[2:3]
	v_pk_mov_b32 v[118:119], v[2:3], v[2:3]
	v_pk_mov_b32 v[120:121], v[2:3], v[2:3]
	v_pk_mov_b32 v[130:131], v[2:3], v[2:3]
	v_pk_mov_b32 v[132:133], v[2:3], v[2:3]
	v_pk_mov_b32 v[134:135], v[2:3], v[2:3]
	v_pk_mov_b32 v[136:137], v[2:3], v[2:3]
	v_pk_mov_b32 v[146:147], v[2:3], v[2:3]
	v_pk_mov_b32 v[148:149], v[2:3], v[2:3]
	v_pk_mov_b32 v[150:151], v[2:3], v[2:3]
	v_pk_mov_b32 v[152:153], v[2:3], v[2:3]
	v_pk_mov_b32 v[106:107], v[2:3], v[2:3]
	v_pk_mov_b32 v[108:109], v[2:3], v[2:3]
	v_pk_mov_b32 v[110:111], v[2:3], v[2:3]
	v_pk_mov_b32 v[112:113], v[2:3], v[2:3]
	v_pk_mov_b32 v[122:123], v[2:3], v[2:3]
	v_pk_mov_b32 v[124:125], v[2:3], v[2:3]
	v_pk_mov_b32 v[126:127], v[2:3], v[2:3]
	v_pk_mov_b32 v[128:129], v[2:3], v[2:3]
	v_pk_mov_b32 v[138:139], v[2:3], v[2:3]
	v_pk_mov_b32 v[140:141], v[2:3], v[2:3]
	v_pk_mov_b32 v[142:143], v[2:3], v[2:3]
	v_pk_mov_b32 v[144:145], v[2:3], v[2:3]
	v_pk_mov_b32 v[154:155], v[2:3], v[2:3]
	v_pk_mov_b32 v[156:157], v[2:3], v[2:3]
	v_pk_mov_b32 v[158:159], v[2:3], v[2:3]
	v_pk_mov_b32 v[160:161], v[2:3], v[2:3]

; template <class Epi, class Sched, bool ALIGN_EPI = false, bool SP2 = false>
; __device__ __forceinline__ void gemm_phase(PG8_LAS unsigned char* lds, const Gemm g, const Sched& S, const Epi& E, int wv) {
;     ...
;         const char* nA = has_next ? (const char*)g.A + (size_t)nxt.pm * tstepA : cA; const char* nB = has_next ? (const char*)g.Bt + (size_t)nxt.pn * tstepB : cB;
; #pragma unroll 1
;         for (int t = 0; t < nt; t += 2) {
;             const bool last = (t == nt - 2);
;             const char* a1 = cA + (size_t)(t + 1) * kstep;
;             const char* a2 = last ? nA : cA + (size_t)(t + 2) * kstep; const char* b2 = last ? nB : cB + (size_t)(t + 2) * kstep;
;             const char* a3 = a2 + kstep; const char* b3 = b2 + kstep;
;     ...
; #pragma unroll
;         for (int a = 0; a < 2; ++a)
; #pragma unroll
;             for (int b = 0; b < 2; ++b)
; #pragma unroll
;                 for (int m = 0; m < 4; ++m)
; #pragma unroll
;                     for (int n = 0; n < 2; ++n) acc[a][b][m][n] = (f32x4){0.f, 0.f, 0.f, 0.f};
.LBB0_1975:
	s_add_u32 s96, s2, 0x100
	v_mov_b32_e32 v2, 0
	s_addc_u32 s97, s3, 0
	s_mov_b32 vcc_lo, -2
	v_mov_b32_e32 v3, v2
	v_pk_mov_b32 v[4:5], v[2:3], v[2:3]
	v_pk_mov_b32 v[6:7], v[2:3], v[2:3]
	v_pk_mov_b32 v[8:9], v[2:3], v[2:3]
	v_pk_mov_b32 v[18:19], v[2:3], v[2:3]
	v_pk_mov_b32 v[20:21], v[2:3], v[2:3]
	v_pk_mov_b32 v[22:23], v[2:3], v[2:3]
	v_pk_mov_b32 v[24:25], v[2:3], v[2:3]
	v_pk_mov_b32 v[34:35], v[2:3], v[2:3]
	v_pk_mov_b32 v[36:37], v[2:3], v[2:3]
	v_pk_mov_b32 v[38:39], v[2:3], v[2:3]
	v_pk_mov_b32 v[40:41], v[2:3], v[2:3]
	v_pk_mov_b32 v[50:51], v[2:3], v[2:3]
	v_pk_mov_b32 v[52:53], v[2:3], v[2:3]
	v_pk_mov_b32 v[54:55], v[2:3], v[2:3]
	v_pk_mov_b32 v[56:57], v[2:3], v[2:3]
	v_pk_mov_b32 v[10:11], v[2:3], v[2:3]
	v_pk_mov_b32 v[12:13], v[2:3], v[2:3]
	v_pk_mov_b32 v[14:15], v[2:3], v[2:3]
	v_pk_mov_b32 v[16:17], v[2:3], v[2:3]
	v_pk_mov_b32 v[26:27], v[2:3], v[2:3]
	v_pk_mov_b32 v[28:29], v[2:3], v[2:3]
	v_pk_mov_b32 v[30:31], v[2:3], v[2:3]
	v_pk_mov_b32 v[32:33], v[2:3], v[2:3]
	v_pk_mov_b32 v[42:43], v[2:3], v[2:3]
	v_pk_mov_b32 v[44:45], v[2:3], v[2:3]
	v_pk_mov_b32 v[46:47], v[2:3], v[2:3]
	v_pk_mov_b32 v[48:49], v[2:3], v[2:3]
	v_pk_mov_b32 v[58:59], v[2:3], v[2:3]
	v_pk_mov_b32 v[60:61], v[2:3], v[2:3]
	v_pk_mov_b32 v[62:63], v[2:3], v[2:3]
	v_pk_mov_b32 v[64:65], v[2:3], v[2:3]
	v_pk_mov_b32 v[66:67], v[2:3], v[2:3]
	v_pk_mov_b32 v[68:69], v[2:3], v[2:3]
	v_pk_mov_b32 v[70:71], v[2:3], v[2:3]
	v_pk_mov_b32 v[72:73], v[2:3], v[2:3]
	v_pk_mov_b32 v[82:83], v[2:3], v[2:3]
	v_pk_mov_b32 v[84:85], v[2:3], v[2:3]
	v_pk_mov_b32 v[86:87], v[2:3], v[2:3]
	v_pk_mov_b32 v[88:89], v[2:3], v[2:3]
	v_pk_mov_b32 v[98:99], v[2:3], v[2:3]
	v_pk_mov_b32 v[100:101], v[2:3], v[2:3]
	v_pk_mov_b32 v[102:103], v[2:3], v[2:3]
	v_pk_mov_b32 v[104:105], v[2:3], v[2:3]
	v_pk_mov_b32 v[114:115], v[2:3], v[2:3]
	v_pk_mov_b32 v[116:117], v[2:3], v[2:3]
	v_pk_mov_b32 v[118:119], v[2:3], v[2:3]
	v_pk_mov_b32 v[120:121], v[2:3], v[2:3]
	v_pk_mov_b32 v[74:75], v[2:3], v[2:3]
	v_pk_mov_b32 v[76:77], v[2:3], v[2:3]
	v_pk_mov_b32 v[78:79], v[2:3], v[2:3]
	v_pk_mov_b32 v[80:81], v[2:3], v[2:3]
	v_pk_mov_b32 v[90:91], v[2:3], v[2:3]
	v_pk_mov_b32 v[92:93], v[2:3], v[2:3]
	v_pk_mov_b32 v[94:95], v[2:3], v[2:3]
	v_pk_mov_b32 v[96:97], v[2:3], v[2:3]
	v_pk_mov_b32 v[106:107], v[2:3], v[2:3]
	v_pk_mov_b32 v[108:109], v[2:3], v[2:3]
	v_pk_mov_b32 v[110:111], v[2:3], v[2:3]
	v_pk_mov_b32 v[112:113], v[2:3], v[2:3]
	v_pk_mov_b32 v[122:123], v[2:3], v[2:3]
	v_pk_mov_b32 v[124:125], v[2:3], v[2:3]
	v_pk_mov_b32 v[126:127], v[2:3], v[2:3]
	v_pk_mov_b32 v[128:129], v[2:3], v[2:3]
